# barrier poll loops sleep 4 instead of 1 (fewer fabric polls while other blocks still compute)
# speedup vs baseline: 1.0034x; 1.0010x over previous
.LBB0_11:
	s_sleep 4
	global_load_dword v2, v1, s[6:7] offset:32 sc1
	s_waitcnt vmcnt(0)
	v_and_b32_e32 v2, 0xffff0000, v2
	v_cmp_ne_u32_e32 vcc, v2, v0
	s_or_b64 s[8:9], vcc, s[8:9]
	s_andn2_b64 exec, exec, s[8:9]
	s_cbranch_execnz .LBB0_11

.LBB0_152:
	global_load_dword v15, v16, s[6:7] sc1
	s_waitcnt lgkmcnt(0)
	global_load_dword v0, v16, s[8:9] sc1
	global_load_dword v1, v16, s[10:11] sc1
	global_load_dword v2, v16, s[12:13] sc1
	global_load_dword v3, v16, s[16:17] sc1
	global_load_dword v4, v16, s[18:19] sc1
	global_load_dword v5, v16, s[20:21] sc1
	global_load_dword v6, v16, s[22:23] sc1
	global_load_dword v7, v16, s[28:29] sc1
	global_load_dword v8, v16, s[30:31] sc1
	global_load_dword v9, v16, s[34:35] sc1
	global_load_dword v10, v16, s[36:37] sc1
	global_load_dword v11, v16, s[38:39] sc1
	global_load_dword v12, v16, s[40:41] sc1
	global_load_dword v13, v16, s[42:43] sc1
	global_load_dword v14, v16, s[44:45] sc1
	s_mov_b64 s[46:47], -1
	s_mov_b64 s[48:49], -1
	s_waitcnt vmcnt(14)
	v_add_u32_e32 v17, v0, v15
	s_waitcnt vmcnt(13)
	v_add_u32_e32 v17, v17, v1
	s_waitcnt vmcnt(12)
	v_add_u32_e32 v17, v17, v2
	s_waitcnt vmcnt(11)
	v_add_u32_e32 v17, v17, v3
	s_waitcnt vmcnt(10)
	v_add_u32_e32 v17, v17, v4
	s_waitcnt vmcnt(9)
	v_add_u32_e32 v17, v17, v5
	s_waitcnt vmcnt(8)
	v_add_u32_e32 v17, v17, v6
	s_waitcnt vmcnt(7)
	v_add_u32_e32 v17, v17, v7
	s_waitcnt vmcnt(6)
	v_add_u32_e32 v17, v17, v8
	s_waitcnt vmcnt(5)
	v_add_u32_e32 v17, v17, v9
	s_waitcnt vmcnt(4)
	v_add_u32_e32 v17, v17, v10
	s_waitcnt vmcnt(3)
	v_add_u32_e32 v17, v17, v11
	s_waitcnt vmcnt(2)
	v_add_u32_e32 v17, v17, v12
	s_waitcnt vmcnt(1)
	v_add_u32_e32 v17, v17, v13
	s_waitcnt vmcnt(0)
	v_add_u32_e32 v17, v17, v14
	v_cmp_eq_u32_e32 vcc, s3, v17
	s_cbranch_vccnz .LBB0_151
	s_and_b32 s46, s33, 0xff
	s_cmp_eq_u32 s46, 0
	s_mov_b64 s[46:47], -1
	s_mov_b64 s[50:51], -1
	s_sleep 4
	s_cbranch_scc1 .LBB0_156
	s_and_b64 vcc, exec, s[50:51]
	s_cbranch_vccz .LBB0_151

.LBB0_170:
	s_and_b32 s28, s3, 0xff
	s_mov_b64 s[22:23], -1
	s_cmp_lg_u32 s28, 0
	s_mov_b64 s[30:31], -1
	s_sleep 4
	s_cbranch_scc0 .LBB0_173
	s_and_b64 vcc, exec, s[30:31]
	s_cbranch_vccz .LBB0_169

.LBB0_187:
	s_and_b32 s28, s3, 0xff
	s_cmp_lg_u32 s28, 0
	s_mov_b64 s[30:31], -1
	s_sleep 4
	s_cbranch_scc0 .LBB0_190
	s_mov_b64 s[34:35], -1
	s_and_b64 vcc, exec, s[30:31]
	s_cbranch_vccz .LBB0_186

.LBB0_241:
	v_readlane_b32 s6, v252, 26
	v_readlane_b32 s7, v252, 27
	global_load_dword v8, v0, s[88:89] sc1
	global_load_dword v1, v0, s[84:85] sc1
	s_waitcnt lgkmcnt(0)
	global_load_dword v2, v0, s[70:71] sc1
	global_load_dword v3, v0, s[72:73] sc1
	global_load_dword v4, v0, s[66:67] sc1
	global_load_dword v5, v0, s[62:63] sc1
	global_load_dword v6, v0, s[64:65] sc1
	global_load_dword v7, v0, s[76:77] sc1
	global_load_dword v9, v0, s[6:7] sc1
	v_readlane_b32 s6, v252, 28
	v_readlane_b32 s7, v252, 29
	s_mov_b64 s[8:9], -1
	s_waitcnt vmcnt(7)
	v_add_u32_e32 v17, v1, v8
	s_nop 1
	global_load_dword v10, v0, s[6:7] sc1
	v_readlane_b32 s6, v252, 30
	v_readlane_b32 s7, v252, 31
	s_waitcnt vmcnt(7)
	v_add_u32_e32 v17, v17, v2
	s_waitcnt vmcnt(6)
	v_add_u32_e32 v17, v17, v3
	s_waitcnt vmcnt(5)
	v_add_u32_e32 v17, v17, v4
	s_waitcnt vmcnt(4)
	v_add_u32_e32 v17, v17, v5
	s_waitcnt vmcnt(3)
	v_add_u32_e32 v17, v17, v6
	global_load_dword v11, v0, s[6:7] sc1
	v_readlane_b32 s6, v252, 57
	v_readlane_b32 s7, v252, 58
	s_waitcnt vmcnt(3)
	v_add_u32_e32 v17, v17, v7
	s_waitcnt vmcnt(2)
	v_add_u32_e32 v17, v17, v9
	s_waitcnt vmcnt(1)
	v_add_u32_e32 v17, v17, v10
	global_load_dword v12, v0, s[6:7] sc1
	v_readlane_b32 s6, v252, 59
	v_readlane_b32 s7, v252, 60
	s_waitcnt vmcnt(1)
	v_add_u32_e32 v17, v17, v11
	s_nop 2
	global_load_dword v13, v0, s[6:7] sc1
	v_readlane_b32 s6, v252, 61
	v_readlane_b32 s7, v252, 62
	s_waitcnt vmcnt(1)
	v_add_u32_e32 v17, v17, v12
	s_nop 2
	global_load_dword v14, v0, s[6:7] sc1
	v_readlane_b32 s6, v252, 63
	v_readlane_b32 s7, v253, 0
	s_waitcnt vmcnt(1)
	v_add_u32_e32 v17, v17, v13
	s_nop 2
	global_load_dword v15, v0, s[6:7] sc1
	v_readlane_b32 s6, v253, 1
	v_readlane_b32 s7, v253, 2
	s_waitcnt vmcnt(1)
	v_add_u32_e32 v17, v17, v14
	s_nop 2
	global_load_dword v16, v0, s[6:7] sc1
	s_mov_b64 s[6:7], -1
	s_waitcnt vmcnt(1)
	v_add_u32_e32 v17, v17, v15
	s_waitcnt vmcnt(0)
	v_add_u32_e32 v17, v17, v16
	v_cmp_eq_u32_e32 vcc, s69, v17
	s_cbranch_vccnz .LBB0_240
	s_and_b32 s6, s12, 0xff
	s_cmp_eq_u32 s6, 0
	s_mov_b64 s[6:7], -1
	s_mov_b64 s[10:11], -1
	s_sleep 4
	s_cbranch_scc1 .LBB0_245
	s_and_b64 vcc, exec, s[10:11]
	s_cbranch_vccz .LBB0_240

.LBB0_257:
	s_and_b32 s16, s3, 0xff
	s_mov_b64 s[14:15], -1
	s_cmp_lg_u32 s16, 0
	s_mov_b64 s[18:19], -1
	s_sleep 4
	s_cbranch_scc0 .LBB0_260
	s_and_b64 vcc, exec, s[18:19]
	s_cbranch_vccz .LBB0_256

.LBB0_340:
	v_readlane_b32 s6, v252, 26
	v_readlane_b32 s7, v252, 27
	global_load_dword v8, v0, s[88:89] sc1
	global_load_dword v1, v0, s[84:85] sc1
	s_waitcnt lgkmcnt(0)
	global_load_dword v2, v0, s[14:15] sc1
	global_load_dword v3, v0, s[16:17] sc1
	global_load_dword v4, v0, s[66:67] sc1
	global_load_dword v5, v0, s[62:63] sc1
	global_load_dword v6, v0, s[64:65] sc1
	global_load_dword v7, v0, s[18:19] sc1
	global_load_dword v9, v0, s[6:7] sc1
	v_readlane_b32 s6, v252, 28
	v_readlane_b32 s7, v252, 29
	s_mov_b64 s[8:9], -1
	s_waitcnt vmcnt(7)
	v_add_u32_e32 v17, v1, v8
	s_nop 1
	global_load_dword v10, v0, s[6:7] sc1
	v_readlane_b32 s6, v252, 30
	v_readlane_b32 s7, v252, 31
	s_waitcnt vmcnt(7)
	v_add_u32_e32 v17, v17, v2
	s_waitcnt vmcnt(6)
	v_add_u32_e32 v17, v17, v3
	s_waitcnt vmcnt(5)
	v_add_u32_e32 v17, v17, v4
	s_waitcnt vmcnt(4)
	v_add_u32_e32 v17, v17, v5
	s_waitcnt vmcnt(3)
	v_add_u32_e32 v17, v17, v6
	global_load_dword v11, v0, s[6:7] sc1
	v_readlane_b32 s6, v252, 57
	v_readlane_b32 s7, v252, 58
	s_waitcnt vmcnt(3)
	v_add_u32_e32 v17, v17, v7
	s_waitcnt vmcnt(2)
	v_add_u32_e32 v17, v17, v9
	s_waitcnt vmcnt(1)
	v_add_u32_e32 v17, v17, v10
	global_load_dword v12, v0, s[6:7] sc1
	v_readlane_b32 s6, v252, 59
	v_readlane_b32 s7, v252, 60
	s_waitcnt vmcnt(1)
	v_add_u32_e32 v17, v17, v11
	s_nop 2
	global_load_dword v13, v0, s[6:7] sc1
	v_readlane_b32 s6, v252, 61
	v_readlane_b32 s7, v252, 62
	s_waitcnt vmcnt(1)
	v_add_u32_e32 v17, v17, v12
	s_nop 2
	global_load_dword v14, v0, s[6:7] sc1
	v_readlane_b32 s6, v252, 63
	v_readlane_b32 s7, v253, 0
	s_waitcnt vmcnt(1)
	v_add_u32_e32 v17, v17, v13
	s_nop 2
	global_load_dword v15, v0, s[6:7] sc1
	v_readlane_b32 s6, v253, 1
	v_readlane_b32 s7, v253, 2
	s_waitcnt vmcnt(1)
	v_add_u32_e32 v17, v17, v14
	s_nop 2
	global_load_dword v16, v0, s[6:7] sc1
	s_mov_b64 s[6:7], -1
	s_waitcnt vmcnt(1)
	v_add_u32_e32 v17, v17, v15
	s_waitcnt vmcnt(0)
	v_add_u32_e32 v17, v17, v16
	v_cmp_eq_u32_e32 vcc, s13, v17
	s_cbranch_vccnz .LBB0_339
	s_and_b32 s6, s12, 0xff
	s_cmp_eq_u32 s6, 0
	s_mov_b64 s[6:7], -1
	s_mov_b64 s[10:11], -1
	s_sleep 4
	s_cbranch_scc1 .LBB0_344
	s_and_b64 vcc, exec, s[10:11]
	s_cbranch_vccz .LBB0_339

.LBB0_843:
	v_readlane_b32 s6, v255, 3
	v_readlane_b32 s7, v255, 4
	s_waitcnt lgkmcnt(0)
	global_load_dword v2, v0, s[88:89] sc1
	global_load_dword v1, v0, s[84:85] sc1
	s_mov_b64 s[8:9], -1
	s_waitcnt vmcnt(0)
	v_add_u32_e32 v17, v1, v2
	global_load_dword v3, v0, s[6:7] sc1
	v_readlane_b32 s6, v255, 5
	v_readlane_b32 s7, v255, 6
	s_nop 4
	global_load_dword v4, v0, s[6:7] sc1
	global_load_dword v5, v0, s[66:67] sc1
	global_load_dword v6, v0, s[62:63] sc1
	global_load_dword v7, v0, s[64:65] sc1
	v_readlane_b32 s6, v255, 13
	v_readlane_b32 s7, v255, 14
	s_waitcnt vmcnt(4)
	v_add_u32_e32 v17, v17, v3
	s_nop 2
	global_load_dword v8, v0, s[6:7] sc1
	v_readlane_b32 s6, v252, 26
	v_readlane_b32 s7, v252, 27
	s_waitcnt vmcnt(4)
	v_add_u32_e32 v17, v17, v4
	s_waitcnt vmcnt(3)
	v_add_u32_e32 v17, v17, v5
	s_waitcnt vmcnt(2)
	v_add_u32_e32 v17, v17, v6
	s_waitcnt vmcnt(1)
	v_add_u32_e32 v17, v17, v7
	s_waitcnt vmcnt(0)
	v_add_u32_e32 v17, v17, v8
	global_load_dword v9, v0, s[6:7] sc1
	v_readlane_b32 s6, v252, 28
	v_readlane_b32 s7, v252, 29
	s_waitcnt vmcnt(0)
	v_add_u32_e32 v17, v17, v9
	s_nop 2
	global_load_dword v10, v0, s[6:7] sc1
	v_readlane_b32 s6, v252, 30
	v_readlane_b32 s7, v252, 31
	s_waitcnt vmcnt(0)
	v_add_u32_e32 v17, v17, v10
	s_nop 2
	global_load_dword v11, v0, s[6:7] sc1
	v_readlane_b32 s6, v252, 57
	v_readlane_b32 s7, v252, 58
	s_waitcnt vmcnt(0)
	v_add_u32_e32 v17, v17, v11
	s_nop 2
	global_load_dword v12, v0, s[6:7] sc1
	v_readlane_b32 s6, v252, 59
	v_readlane_b32 s7, v252, 60
	s_waitcnt vmcnt(0)
	v_add_u32_e32 v17, v17, v12
	s_nop 2
	global_load_dword v13, v0, s[6:7] sc1
	v_readlane_b32 s6, v252, 61
	v_readlane_b32 s7, v252, 62
	s_waitcnt vmcnt(0)
	v_add_u32_e32 v17, v17, v13
	s_nop 2
	global_load_dword v14, v0, s[6:7] sc1
	v_readlane_b32 s6, v252, 63
	v_readlane_b32 s7, v253, 0
	s_waitcnt vmcnt(0)
	v_add_u32_e32 v17, v17, v14
	s_nop 2
	global_load_dword v15, v0, s[6:7] sc1
	v_readlane_b32 s6, v253, 1
	v_readlane_b32 s7, v253, 2
	s_waitcnt vmcnt(0)
	v_add_u32_e32 v17, v17, v15
	s_nop 2
	global_load_dword v16, v0, s[6:7] sc1
	s_mov_b64 s[6:7], -1
	s_waitcnt vmcnt(0)
	v_add_u32_e32 v17, v17, v16
	v_cmp_eq_u32_e32 vcc, s82, v17
	s_cbranch_vccnz .LBB0_842
	s_and_b32 s6, s12, 0xff
	s_cmp_eq_u32 s6, 0
	s_mov_b64 s[6:7], -1
	s_mov_b64 s[10:11], -1
	s_sleep 4
	s_cbranch_scc1 .LBB0_847
	s_and_b64 vcc, exec, s[10:11]
	s_cbranch_vccz .LBB0_842

.LBB0_986:
	v_readlane_b32 s6, v255, 13
	v_readlane_b32 s7, v255, 14
	global_load_dword v7, v0, s[88:89] sc1
	global_load_dword v1, v0, s[84:85] sc1
	s_waitcnt lgkmcnt(0)
	global_load_dword v2, v0, s[20:21] sc1
	global_load_dword v3, v0, s[28:29] sc1
	global_load_dword v4, v0, s[66:67] sc1
	global_load_dword v5, v0, s[62:63] sc1
	global_load_dword v6, v0, s[64:65] sc1
	global_load_dword v8, v0, s[6:7] sc1
	v_readlane_b32 s6, v252, 26
	v_readlane_b32 s7, v252, 27
	s_mov_b64 s[8:9], -1
	s_waitcnt vmcnt(6)
	v_add_u32_e32 v17, v1, v7
	s_nop 1
	global_load_dword v9, v0, s[6:7] sc1
	v_readlane_b32 s6, v252, 28
	v_readlane_b32 s7, v252, 29
	s_waitcnt vmcnt(6)
	v_add_u32_e32 v17, v17, v2
	s_waitcnt vmcnt(5)
	v_add_u32_e32 v17, v17, v3
	s_waitcnt vmcnt(4)
	v_add_u32_e32 v17, v17, v4
	s_waitcnt vmcnt(3)
	v_add_u32_e32 v17, v17, v5
	s_waitcnt vmcnt(2)
	v_add_u32_e32 v17, v17, v6
	global_load_dword v10, v0, s[6:7] sc1
	v_readlane_b32 s6, v252, 30
	v_readlane_b32 s7, v252, 31
	s_waitcnt vmcnt(2)
	v_add_u32_e32 v17, v17, v8
	s_waitcnt vmcnt(1)
	v_add_u32_e32 v17, v17, v9
	s_nop 0
	global_load_dword v11, v0, s[6:7] sc1
	v_readlane_b32 s6, v252, 57
	v_readlane_b32 s7, v252, 58
	s_waitcnt vmcnt(1)
	v_add_u32_e32 v17, v17, v10
	s_nop 2
	global_load_dword v12, v0, s[6:7] sc1
	v_readlane_b32 s6, v252, 59
	v_readlane_b32 s7, v252, 60
	s_waitcnt vmcnt(1)
	v_add_u32_e32 v17, v17, v11
	s_nop 2
	global_load_dword v13, v0, s[6:7] sc1
	v_readlane_b32 s6, v252, 61
	v_readlane_b32 s7, v252, 62
	s_waitcnt vmcnt(1)
	v_add_u32_e32 v17, v17, v12
	s_nop 2
	global_load_dword v14, v0, s[6:7] sc1
	v_readlane_b32 s6, v252, 63
	v_readlane_b32 s7, v253, 0
	s_waitcnt vmcnt(1)
	v_add_u32_e32 v17, v17, v13
	s_nop 2
	global_load_dword v15, v0, s[6:7] sc1
	v_readlane_b32 s6, v253, 1
	v_readlane_b32 s7, v253, 2
	s_waitcnt vmcnt(1)
	v_add_u32_e32 v17, v17, v14
	s_nop 2
	global_load_dword v16, v0, s[6:7] sc1
	s_mov_b64 s[6:7], -1
	s_waitcnt vmcnt(1)
	v_add_u32_e32 v17, v17, v15
	s_waitcnt vmcnt(0)
	v_add_u32_e32 v17, v17, v16
	v_cmp_eq_u32_e32 vcc, s82, v17
	s_cbranch_vccnz .LBB0_985
	s_and_b32 s6, s12, 0xff
	s_cmp_eq_u32 s6, 0
	s_mov_b64 s[6:7], -1
	s_mov_b64 s[10:11], -1
	s_sleep 4
	s_cbranch_scc1 .LBB0_990
	s_and_b64 vcc, exec, s[10:11]
	s_cbranch_vccz .LBB0_985

.LBB0_1113:
	v_readlane_b32 s28, v252, 26
	v_readlane_b32 s29, v252, 27
	global_load_dword v8, v0, s[88:89] sc1
	global_load_dword v1, v0, s[84:85] sc1
	s_waitcnt lgkmcnt(0)
	global_load_dword v2, v0, s[70:71] sc1
	global_load_dword v3, v0, s[72:73] sc1
	global_load_dword v4, v0, s[66:67] sc1
	global_load_dword v5, v0, s[62:63] sc1
	global_load_dword v6, v0, s[64:65] sc1
	global_load_dword v7, v0, s[76:77] sc1
	global_load_dword v9, v0, s[28:29] sc1
	v_readlane_b32 s28, v252, 28
	v_readlane_b32 s29, v252, 29
	s_mov_b64 s[36:37], -1
	s_waitcnt vmcnt(7)
	v_add_u32_e32 v17, v1, v8
	s_nop 1
	global_load_dword v10, v0, s[28:29] sc1
	v_readlane_b32 s28, v252, 30
	v_readlane_b32 s29, v252, 31
	s_waitcnt vmcnt(7)
	v_add_u32_e32 v17, v17, v2
	s_waitcnt vmcnt(6)
	v_add_u32_e32 v17, v17, v3
	s_waitcnt vmcnt(5)
	v_add_u32_e32 v17, v17, v4
	s_waitcnt vmcnt(4)
	v_add_u32_e32 v17, v17, v5
	s_waitcnt vmcnt(3)
	v_add_u32_e32 v17, v17, v6
	global_load_dword v11, v0, s[28:29] sc1
	v_readlane_b32 s28, v252, 57
	v_readlane_b32 s29, v252, 58
	s_waitcnt vmcnt(3)
	v_add_u32_e32 v17, v17, v7
	s_waitcnt vmcnt(2)
	v_add_u32_e32 v17, v17, v9
	s_waitcnt vmcnt(1)
	v_add_u32_e32 v17, v17, v10
	global_load_dword v12, v0, s[28:29] sc1
	v_readlane_b32 s28, v252, 59
	v_readlane_b32 s29, v252, 60
	s_waitcnt vmcnt(1)
	v_add_u32_e32 v17, v17, v11
	s_nop 2
	global_load_dword v13, v0, s[28:29] sc1
	v_readlane_b32 s28, v252, 61
	v_readlane_b32 s29, v252, 62
	s_waitcnt vmcnt(1)
	v_add_u32_e32 v17, v17, v12
	s_nop 2
	global_load_dword v14, v0, s[28:29] sc1
	v_readlane_b32 s28, v252, 63
	v_readlane_b32 s29, v253, 0
	s_waitcnt vmcnt(1)
	v_add_u32_e32 v17, v17, v13
	s_nop 2
	global_load_dword v15, v0, s[28:29] sc1
	v_readlane_b32 s28, v253, 1
	v_readlane_b32 s29, v253, 2
	s_waitcnt vmcnt(1)
	v_add_u32_e32 v17, v17, v14
	s_nop 2
	global_load_dword v16, v0, s[28:29] sc1
	s_mov_b64 s[28:29], -1
	s_waitcnt vmcnt(1)
	v_add_u32_e32 v17, v17, v15
	s_waitcnt vmcnt(0)
	v_add_u32_e32 v17, v17, v16
	v_cmp_eq_u32_e32 vcc, s69, v17
	s_cbranch_vccnz .LBB0_1112
	s_and_b32 s28, s27, 0xff
	s_cmp_eq_u32 s28, 0
	s_mov_b64 s[28:29], -1
	s_mov_b64 s[42:43], -1
	s_sleep 4
	s_cbranch_scc1 .LBB0_1117
	s_and_b64 vcc, exec, s[42:43]
	s_cbranch_vccz .LBB0_1112

.LBB0_1129:
	s_and_b32 s27, s3, 0xff
	s_mov_b64 s[48:49], -1
	s_cmp_lg_u32 s27, 0
	s_mov_b64 s[52:53], -1
	s_sleep 4
	s_cbranch_scc0 .LBB0_1132
	s_and_b64 vcc, exec, s[52:53]
	s_cbranch_vccz .LBB0_1128

.LBB0_1240:
	v_readlane_b32 s28, v252, 26
	v_readlane_b32 s29, v252, 27
	global_load_dword v8, v0, s[88:89] sc1
	global_load_dword v1, v0, s[84:85] sc1
	s_waitcnt lgkmcnt(0)
	global_load_dword v2, v0, s[70:71] sc1
	global_load_dword v3, v0, s[72:73] sc1
	global_load_dword v4, v0, s[66:67] sc1
	global_load_dword v5, v0, s[62:63] sc1
	global_load_dword v6, v0, s[64:65] sc1
	global_load_dword v7, v0, s[76:77] sc1
	global_load_dword v9, v0, s[28:29] sc1
	v_readlane_b32 s28, v252, 28
	v_readlane_b32 s29, v252, 29
	s_mov_b64 s[36:37], -1
	s_waitcnt vmcnt(7)
	v_add_u32_e32 v17, v1, v8
	s_nop 1
	global_load_dword v10, v0, s[28:29] sc1
	v_readlane_b32 s28, v252, 30
	v_readlane_b32 s29, v252, 31
	s_waitcnt vmcnt(7)
	v_add_u32_e32 v17, v17, v2
	s_waitcnt vmcnt(6)
	v_add_u32_e32 v17, v17, v3
	s_waitcnt vmcnt(5)
	v_add_u32_e32 v17, v17, v4
	s_waitcnt vmcnt(4)
	v_add_u32_e32 v17, v17, v5
	s_waitcnt vmcnt(3)
	v_add_u32_e32 v17, v17, v6
	global_load_dword v11, v0, s[28:29] sc1
	v_readlane_b32 s28, v252, 57
	v_readlane_b32 s29, v252, 58
	s_waitcnt vmcnt(3)
	v_add_u32_e32 v17, v17, v7
	s_waitcnt vmcnt(2)
	v_add_u32_e32 v17, v17, v9
	s_waitcnt vmcnt(1)
	v_add_u32_e32 v17, v17, v10
	global_load_dword v12, v0, s[28:29] sc1
	v_readlane_b32 s28, v252, 59
	v_readlane_b32 s29, v252, 60
	s_waitcnt vmcnt(1)
	v_add_u32_e32 v17, v17, v11
	s_nop 2
	global_load_dword v13, v0, s[28:29] sc1
	v_readlane_b32 s28, v252, 61
	v_readlane_b32 s29, v252, 62
	s_waitcnt vmcnt(1)
	v_add_u32_e32 v17, v17, v12
	s_nop 2
	global_load_dword v14, v0, s[28:29] sc1
	v_readlane_b32 s28, v252, 63
	v_readlane_b32 s29, v253, 0
	s_waitcnt vmcnt(1)
	v_add_u32_e32 v17, v17, v13
	s_nop 2
	global_load_dword v15, v0, s[28:29] sc1
	v_readlane_b32 s28, v253, 1
	v_readlane_b32 s29, v253, 2
	s_waitcnt vmcnt(1)
	v_add_u32_e32 v17, v17, v14
	s_nop 2
	global_load_dword v16, v0, s[28:29] sc1
	s_mov_b64 s[28:29], -1
	s_waitcnt vmcnt(1)
	v_add_u32_e32 v17, v17, v15
	s_waitcnt vmcnt(0)
	v_add_u32_e32 v17, v17, v16
	v_cmp_eq_u32_e32 vcc, s69, v17
	s_cbranch_vccnz .LBB0_1239
	s_and_b32 s28, s27, 0xff
	s_cmp_eq_u32 s28, 0
	s_mov_b64 s[28:29], -1
	s_mov_b64 s[40:41], -1
	s_sleep 4
	s_cbranch_scc1 .LBB0_1244
	s_and_b64 vcc, exec, s[40:41]
	s_cbranch_vccz .LBB0_1239
